# xattn-Q, KV-proj and up-proj MERGED epilogues: dwordx2 pieces paired via v_permlane16_swap into dwordx4 stores
# speedup vs baseline: 1.0386x; 1.0107x over previous
.Lkx_238:
	s_mov_b32 s2, 0x18000
	v_add3_u32 v144, v134, v135, s2
	v_add3_u32 v135, v132, v135, s81
	ds_read_b128 v[128:131], v144
	ds_read_b128 v[136:139], v144 offset:2048
	ds_read_b128 v[140:143], v144 offset:4096
	ds_read_b128 v[146:149], v144 offset:6144
	ds_read_b128 v[154:157], v135
	ds_read_b128 v[158:161], v135 offset:2048
	ds_read_b128 v[162:165], v135 offset:4096
	ds_read_b128 v[166:169], v135 offset:6144
	ds_read_b128 v[170:173], v135 offset:8192
	ds_read_b128 v[174:177], v135 offset:10240
	ds_read_b128 v[178:181], v135 offset:12288
	ds_read_b128 v[182:185], v135 offset:14336
	s_waitcnt lgkmcnt(7)
	v_mfma_f32_16x16x32_bf16 v[124:127], v[128:131], v[154:157], v[124:127]
	v_mfma_f32_16x16x32_bf16 v[120:123], v[136:139], v[154:157], v[120:123]
	v_mfma_f32_16x16x32_bf16 v[116:119], v[140:143], v[154:157], v[116:119]
	v_mfma_f32_16x16x32_bf16 v[112:115], v[146:149], v[154:157], v[112:115]
	s_waitcnt lgkmcnt(6)
	v_mfma_f32_16x16x32_bf16 v[108:111], v[128:131], v[158:161], v[108:111]
	v_mfma_f32_16x16x32_bf16 v[104:107], v[136:139], v[158:161], v[104:107]
	v_mfma_f32_16x16x32_bf16 v[100:103], v[140:143], v[158:161], v[100:103]
	v_mfma_f32_16x16x32_bf16 v[96:99], v[146:149], v[158:161], v[96:99]
	s_waitcnt lgkmcnt(5)
	v_mfma_f32_16x16x32_bf16 v[92:95], v[128:131], v[162:165], v[92:95]
	v_mfma_f32_16x16x32_bf16 v[84:87], v[136:139], v[162:165], v[84:87]
	v_mfma_f32_16x16x32_bf16 v[80:83], v[140:143], v[162:165], v[80:83]
	v_mfma_f32_16x16x32_bf16 v[76:79], v[146:149], v[162:165], v[76:79]
	s_waitcnt lgkmcnt(4)
	v_mfma_f32_16x16x32_bf16 v[72:75], v[128:131], v[166:169], v[72:75]
	v_mfma_f32_16x16x32_bf16 v[68:71], v[136:139], v[166:169], v[68:71]
	v_mfma_f32_16x16x32_bf16 v[64:67], v[140:143], v[166:169], v[64:67]
	v_mfma_f32_16x16x32_bf16 v[60:63], v[146:149], v[166:169], v[60:63]
	v_add3_u32 v134, v134, v133, s2
	v_add3_u32 v144, v132, v133, s81
	ds_read_b128 v[154:157], v134
	ds_read_b128 v[158:161], v134 offset:2048
	ds_read_b128 v[162:165], v134 offset:4096
	ds_read_b128 v[166:169], v134 offset:6144
	ds_read_b128 v[132:135], v144
	ds_read_b128 v[186:189], v144 offset:2048
	ds_read_b128 v[206:209], v144 offset:4096
	ds_read_b128 v[216:219], v144 offset:6144
	s_waitcnt lgkmcnt(11)
	v_mfma_f32_16x16x32_bf16 v[56:59], v[128:131], v[170:173], v[56:59]
	v_mfma_f32_16x16x32_bf16 v[52:55], v[136:139], v[170:173], v[52:55]
	v_mfma_f32_16x16x32_bf16 v[48:51], v[140:143], v[170:173], v[48:51]
	v_mfma_f32_16x16x32_bf16 v[44:47], v[146:149], v[170:173], v[44:47]
	s_waitcnt lgkmcnt(10)
	v_mfma_f32_16x16x32_bf16 v[40:43], v[128:131], v[174:177], v[40:43]
	v_mfma_f32_16x16x32_bf16 v[36:39], v[136:139], v[174:177], v[36:39]
	v_mfma_f32_16x16x32_bf16 v[32:35], v[140:143], v[174:177], v[32:35]
	v_mfma_f32_16x16x32_bf16 v[28:31], v[146:149], v[174:177], v[28:31]
	s_waitcnt lgkmcnt(9)
	v_mfma_f32_16x16x32_bf16 v[24:27], v[128:131], v[178:181], v[24:27]
	v_mfma_f32_16x16x32_bf16 v[20:23], v[136:139], v[178:181], v[20:23]
	v_mfma_f32_16x16x32_bf16 v[16:19], v[140:143], v[178:181], v[16:19]
	v_mfma_f32_16x16x32_bf16 v[12:15], v[146:149], v[178:181], v[12:15]
	s_waitcnt lgkmcnt(8)
	v_mfma_f32_16x16x32_bf16 v[8:11], v[128:131], v[182:185], v[8:11]
	v_mfma_f32_16x16x32_bf16 v[4:7], v[136:139], v[182:185], v[4:7]
	v_mfma_f32_16x16x32_bf16 v[0:3], v[140:143], v[182:185], v[0:3]
	v_mfma_f32_16x16x32_bf16 v[128:131], v[146:149], v[182:185], v[88:91]
	ds_read_b128 v[136:139], v144 offset:8192
	ds_read_b128 v[140:143], v144 offset:10240
	ds_read_b128 v[146:149], v144 offset:12288
	ds_read_b128 v[170:173], v144 offset:14336
	s_waitcnt lgkmcnt(7)
	v_mfma_f32_16x16x32_bf16 v[124:127], v[154:157], v[132:135], v[124:127]
	v_mfma_f32_16x16x32_bf16 v[120:123], v[158:161], v[132:135], v[120:123]
	v_mfma_f32_16x16x32_bf16 v[116:119], v[162:165], v[132:135], v[116:119]
	v_mfma_f32_16x16x32_bf16 v[112:115], v[166:169], v[132:135], v[112:115]
	s_waitcnt lgkmcnt(6)
	v_mfma_f32_16x16x32_bf16 v[108:111], v[154:157], v[186:189], v[108:111]
	v_mfma_f32_16x16x32_bf16 v[132:135], v[158:161], v[186:189], v[104:107]
	v_mfma_f32_16x16x32_bf16 v[174:177], v[162:165], v[186:189], v[100:103]
	v_mfma_f32_16x16x32_bf16 v[96:99], v[166:169], v[186:189], v[96:99]
	s_waitcnt lgkmcnt(5)
	v_mfma_f32_16x16x32_bf16 v[92:95], v[154:157], v[206:209], v[92:95]
	v_mfma_f32_16x16x32_bf16 v[88:91], v[158:161], v[206:209], v[84:87]
	v_mfma_f32_16x16x32_bf16 v[84:87], v[162:165], v[206:209], v[80:83]
	v_mfma_f32_16x16x32_bf16 v[80:83], v[166:169], v[206:209], v[76:79]
	s_waitcnt lgkmcnt(4)
	v_mfma_f32_16x16x32_bf16 v[76:79], v[154:157], v[216:219], v[72:75]
	v_mfma_f32_16x16x32_bf16 v[72:75], v[158:161], v[216:219], v[68:71]
	v_mfma_f32_16x16x32_bf16 v[68:71], v[162:165], v[216:219], v[64:67]
	v_mfma_f32_16x16x32_bf16 v[64:67], v[166:169], v[216:219], v[60:63]
	v_mov_b32_e32 v101, v190
	s_lshl_b32 s2, s8, 8
	v_ashrrev_i32_e32 v100, 1, v101
	v_and_b32_e32 v103, 15, v101
	v_and_b32_e32 v104, 0xffffff80, v100
	v_or_b32_e32 v100, s6, v103
	v_or_b32_e32 v103, v104, v103
	v_add_u32_e32 v100, v100, v104
	v_lshl_add_u32 v104, v103, 2, v205
	s_ashr_i32 s3, s2, 31
	s_lshl_b64 s[2:3], s[2:3], 1
	ds_read_b32 v106, v104
	v_and_b32_e32 v102, 0xc0, v101
	s_add_u32 s2, s27, s2
	s_addc_u32 s3, s28, s3
	v_lshlrev_b32_e32 v144, 1, v102
	v_lshrrev_b32_e32 v101, 1, v101
	v_lshl_add_u64 v[102:103], s[2:3], 0, v[144:145]
	v_and_b32_e32 v144, 24, v101
	v_ashrrev_i32_e32 v101, 31, v100
	s_waitcnt lgkmcnt(4)
	v_mfma_f32_16x16x32_bf16 v[60:63], v[154:157], v[136:139], v[56:59]
	v_lshl_add_u64 v[102:103], v[102:103], 0, v[144:145]
	s_waitcnt lgkmcnt(0)
	v_pk_mul_f32 v[126:127], v[126:127], v[106:107] op_sel_hi:[1,0]
	v_pk_mul_f32 v[124:125], v[124:125], v[106:107] op_sel_hi:[1,0]
	v_mfma_f32_16x16x32_bf16 v[56:59], v[158:161], v[136:139], v[52:55]
	v_mul_f32_e64 v122, v122, v106
	v_mul_f32_e64 v123, v123, v106
	v_pk_mul_f32 v[120:121], v[120:121], v[106:107] op_sel_hi:[1,0]
	v_pk_mul_f32 v[118:119], v[118:119], v[106:107] op_sel_hi:[1,0]
	v_mfma_f32_16x16x32_bf16 v[52:55], v[162:165], v[136:139], v[48:51]
	v_mul_f32_e64 v116, v116, v106
	v_mul_f32_e64 v117, v117, v106
	v_pk_mul_f32 v[114:115], v[114:115], v[106:107] op_sel_hi:[1,0]
	v_pk_mul_f32 v[106:107], v[112:113], v[106:107] op_sel_hi:[1,0]
	v_mfma_f32_16x16x32_bf16 v[48:51], v[166:169], v[136:139], v[44:47]
	v_cvt_pk_bf16_f32 v124, v124, v125
	v_cvt_pk_bf16_f32 v125, v126, v127
	v_cvt_pk_bf16_f32 v120, v120, v121
	v_mfma_f32_16x16x32_bf16 v[44:47], v[154:157], v[140:143], v[40:43]
	v_cvt_pk_bf16_f32 v121, v122, v123
	v_cvt_pk_bf16_f32 v116, v116, v117
	v_cvt_pk_bf16_f32 v117, v118, v119
	v_mfma_f32_16x16x32_bf16 v[40:43], v[158:161], v[140:143], v[36:39]
	v_cvt_pk_bf16_f32 v106, v106, v107
	v_cvt_pk_bf16_f32 v107, v114, v115
	v_readlane_b32 s2, v255, 6
	v_mfma_f32_16x16x32_bf16 v[36:39], v[162:165], v[140:143], v[32:35]
	s_add_i32 s30, s30, s72
	s_add_i32 s29, s29, s2
	s_cmpk_gt_i32 s30, 0xff
	v_mfma_f32_16x16x32_bf16 v[32:35], v[166:169], v[140:143], v[28:31]
	v_readlane_b32 s3, v255, 7
	v_mfma_f32_16x16x32_bf16 v[28:31], v[154:157], v[146:149], v[24:27]
	v_mfma_f32_16x16x32_bf16 v[24:27], v[158:161], v[146:149], v[20:23]
	v_mfma_f32_16x16x32_bf16 v[20:23], v[162:165], v[146:149], v[16:19]
	v_mfma_f32_16x16x32_bf16 v[16:19], v[166:169], v[146:149], v[12:15]
	v_mfma_f32_16x16x32_bf16 v[12:15], v[154:157], v[170:173], v[8:11]
	v_mfma_f32_16x16x32_bf16 v[8:11], v[158:161], v[170:173], v[4:7]
	v_mfma_f32_16x16x32_bf16 v[4:7], v[162:165], v[170:173], v[0:3]
	v_mfma_f32_16x16x32_bf16 v[0:3], v[166:169], v[170:173], v[128:131]
	s_nop 2
	v_lshlrev_b64 v[128:129], 11, v[100:101]
	v_lshl_add_u64 v[128:129], v[102:103], 0, v[128:129]
	v_mov_b32_e32 v248, v124
	v_mov_b32_e32 v249, v125
	v_mov_b32_e32 v250, v120
	v_mov_b32_e32 v251, v121
	v_mov_b32_e32 v244, v116
	v_mov_b32_e32 v245, v117
	v_mov_b32_e32 v246, v106
	v_mov_b32_e32 v247, v107
	v_and_b32_e32 v242, 16, v190
	v_mul_u32_u24_e32 v242, 3, v242
	v_lshrrev_b32_e32 v242, 1, v242
	v_mov_b32_e32 v243, 0
	v_lshl_add_u64 v[240:241], v[128:129], 0, v[242:243]
	v_permlane16_swap_b32 v248, v250
	v_permlane16_swap_b32 v249, v251
	v_permlane16_swap_b32 v244, v246
	v_permlane16_swap_b32 v245, v247
	flat_store_dwordx4 v[240:241], v[248:251]
	flat_store_dwordx4 v[240:241], v[244:247] offset:64
	ds_read_b32 v112, v104 offset:64
	v_or_b32_e32 v106, 16, v100
	v_ashrrev_i32_e32 v107, 31, v106
	v_lshlrev_b64 v[106:107], 11, v[106:107]
	v_lshl_add_u64 v[106:107], v[102:103], 0, v[106:107]
	s_waitcnt lgkmcnt(0)
	v_pk_mul_f32 v[110:111], v[110:111], v[112:113] op_sel_hi:[1,0]
	v_pk_mul_f32 v[108:109], v[108:109], v[112:113] op_sel_hi:[1,0]
	v_pk_mul_f32 v[96:97], v[96:97], v[112:113] op_sel_hi:[1,0]
	v_cvt_pk_bf16_f32 v108, v108, v109
	v_cvt_pk_bf16_f32 v109, v110, v111
	v_pk_mul_f32 v[110:111], v[132:133], v[112:113] op_sel_hi:[1,0]
	v_mov_b32_e32 v248, v108
	v_mov_b32_e32 v249, v109
	v_pk_mul_f32 v[108:109], v[134:135], v[112:113] op_sel_hi:[1,0]
	v_cvt_pk_bf16_f32 v110, v110, v111
	v_pk_mul_f32 v[98:99], v[98:99], v[112:113] op_sel_hi:[1,0]
	v_cvt_pk_bf16_f32 v111, v108, v109
	v_mov_b32_e32 v250, v110
	v_mov_b32_e32 v251, v111
	v_pk_mul_f32 v[110:111], v[174:175], v[112:113] op_sel_hi:[1,0]
	v_pk_mul_f32 v[108:109], v[176:177], v[112:113] op_sel_hi:[1,0]
	v_cvt_pk_bf16_f32 v110, v110, v111
	v_cvt_pk_bf16_f32 v96, v96, v97
	v_cvt_pk_bf16_f32 v97, v98, v99
	v_mov_b32_e32 v246, v96
	v_mov_b32_e32 v247, v97
	v_cvt_pk_bf16_f32 v111, v108, v109
	v_mov_b32_e32 v244, v110
	v_mov_b32_e32 v245, v111
	v_and_b32_e32 v242, 16, v190
	v_mul_u32_u24_e32 v242, 3, v242
	v_lshrrev_b32_e32 v242, 1, v242
	v_mov_b32_e32 v243, 0
	v_lshl_add_u64 v[240:241], v[106:107], 0, v[242:243]
	v_permlane16_swap_b32 v248, v250
	v_permlane16_swap_b32 v249, v251
	v_permlane16_swap_b32 v244, v246
	v_permlane16_swap_b32 v245, v247
	flat_store_dwordx4 v[240:241], v[248:251]
	flat_store_dwordx4 v[240:241], v[244:247] offset:64
	ds_read_b32 v98, v104 offset:128
	v_or_b32_e32 v96, 32, v100
	v_ashrrev_i32_e32 v97, 31, v96
	v_lshlrev_b64 v[96:97], 11, v[96:97]
	v_lshl_add_u64 v[96:97], v[102:103], 0, v[96:97]
	s_waitcnt lgkmcnt(0)
	v_pk_mul_f32 v[92:93], v[92:93], v[98:99] op_sel_hi:[1,0]
	v_pk_mul_f32 v[88:89], v[88:89], v[98:99] op_sel_hi:[1,0]
	v_pk_mul_f32 v[84:85], v[84:85], v[98:99] op_sel_hi:[1,0]
	v_pk_mul_f32 v[80:81], v[80:81], v[98:99] op_sel_hi:[1,0]
	v_pk_mul_f32 v[94:95], v[94:95], v[98:99] op_sel_hi:[1,0]
	v_cvt_pk_bf16_f32 v92, v92, v93
	v_pk_mul_f32 v[90:91], v[90:91], v[98:99] op_sel_hi:[1,0]
	v_cvt_pk_bf16_f32 v93, v94, v95
	v_mov_b32_e32 v248, v92
	v_mov_b32_e32 v249, v93
	v_cvt_pk_bf16_f32 v88, v88, v89
	v_cvt_pk_bf16_f32 v89, v90, v91
	v_mov_b32_e32 v250, v88
	v_mov_b32_e32 v251, v89
	v_pk_mul_f32 v[86:87], v[86:87], v[98:99] op_sel_hi:[1,0]
	v_cvt_pk_bf16_f32 v84, v84, v85
	v_pk_mul_f32 v[82:83], v[82:83], v[98:99] op_sel_hi:[1,0]
	v_cvt_pk_bf16_f32 v85, v86, v87
	v_mov_b32_e32 v244, v84
	v_mov_b32_e32 v245, v85
	v_cvt_pk_bf16_f32 v80, v80, v81
	v_cvt_pk_bf16_f32 v81, v82, v83
	v_mov_b32_e32 v246, v80
	v_mov_b32_e32 v247, v81
	v_and_b32_e32 v242, 16, v190
	v_mul_u32_u24_e32 v242, 3, v242
	v_lshrrev_b32_e32 v242, 1, v242
	v_mov_b32_e32 v243, 0
	v_lshl_add_u64 v[240:241], v[96:97], 0, v[242:243]
	v_permlane16_swap_b32 v248, v250
	v_permlane16_swap_b32 v249, v251
	v_permlane16_swap_b32 v244, v246
	v_permlane16_swap_b32 v245, v247
	flat_store_dwordx4 v[240:241], v[248:251]
	flat_store_dwordx4 v[240:241], v[244:247] offset:64
	ds_read_b32 v82, v104 offset:192
	v_or_b32_e32 v80, 48, v100
	v_ashrrev_i32_e32 v81, 31, v80
	v_lshlrev_b64 v[80:81], 11, v[80:81]
	v_lshl_add_u64 v[80:81], v[102:103], 0, v[80:81]
	s_waitcnt lgkmcnt(0)
	v_pk_mul_f32 v[76:77], v[76:77], v[82:83] op_sel_hi:[1,0]
	v_pk_mul_f32 v[72:73], v[72:73], v[82:83] op_sel_hi:[1,0]
	v_pk_mul_f32 v[68:69], v[68:69], v[82:83] op_sel_hi:[1,0]
	v_pk_mul_f32 v[64:65], v[64:65], v[82:83] op_sel_hi:[1,0]
	v_pk_mul_f32 v[78:79], v[78:79], v[82:83] op_sel_hi:[1,0]
	v_cvt_pk_bf16_f32 v76, v76, v77
	v_pk_mul_f32 v[74:75], v[74:75], v[82:83] op_sel_hi:[1,0]
	v_cvt_pk_bf16_f32 v77, v78, v79
	v_mov_b32_e32 v248, v76
	v_mov_b32_e32 v249, v77
	v_cvt_pk_bf16_f32 v72, v72, v73
	v_cvt_pk_bf16_f32 v73, v74, v75
	v_mov_b32_e32 v250, v72
	v_mov_b32_e32 v251, v73
	v_pk_mul_f32 v[70:71], v[70:71], v[82:83] op_sel_hi:[1,0]
	v_cvt_pk_bf16_f32 v68, v68, v69
	v_pk_mul_f32 v[66:67], v[66:67], v[82:83] op_sel_hi:[1,0]
	v_cvt_pk_bf16_f32 v69, v70, v71
	v_mov_b32_e32 v244, v68
	v_mov_b32_e32 v245, v69
	v_cvt_pk_bf16_f32 v64, v64, v65
	v_cvt_pk_bf16_f32 v65, v66, v67
	v_mov_b32_e32 v246, v64
	v_mov_b32_e32 v247, v65
	v_and_b32_e32 v242, 16, v190
	v_mul_u32_u24_e32 v242, 3, v242
	v_lshrrev_b32_e32 v242, 1, v242
	v_mov_b32_e32 v243, 0
	v_lshl_add_u64 v[240:241], v[80:81], 0, v[242:243]
	v_permlane16_swap_b32 v248, v250
	v_permlane16_swap_b32 v249, v251
	v_permlane16_swap_b32 v244, v246
	v_permlane16_swap_b32 v245, v247
	flat_store_dwordx4 v[240:241], v[248:251]
	flat_store_dwordx4 v[240:241], v[244:247] offset:64
	ds_read_b32 v66, v104 offset:256
	v_or_b32_e32 v64, 64, v100
	v_ashrrev_i32_e32 v65, 31, v64
	v_lshlrev_b64 v[64:65], 11, v[64:65]
	v_lshl_add_u64 v[64:65], v[102:103], 0, v[64:65]
	s_waitcnt lgkmcnt(0)
	v_pk_mul_f32 v[60:61], v[60:61], v[66:67] op_sel_hi:[1,0]
	v_pk_mul_f32 v[56:57], v[56:57], v[66:67] op_sel_hi:[1,0]
	v_pk_mul_f32 v[52:53], v[52:53], v[66:67] op_sel_hi:[1,0]
	v_pk_mul_f32 v[48:49], v[48:49], v[66:67] op_sel_hi:[1,0]
	v_pk_mul_f32 v[62:63], v[62:63], v[66:67] op_sel_hi:[1,0]
	v_cvt_pk_bf16_f32 v60, v60, v61
	v_pk_mul_f32 v[58:59], v[58:59], v[66:67] op_sel_hi:[1,0]
	v_cvt_pk_bf16_f32 v61, v62, v63
	v_mov_b32_e32 v248, v60
	v_mov_b32_e32 v249, v61
	v_cvt_pk_bf16_f32 v56, v56, v57
	v_cvt_pk_bf16_f32 v57, v58, v59
	v_mov_b32_e32 v250, v56
	v_mov_b32_e32 v251, v57
	v_pk_mul_f32 v[54:55], v[54:55], v[66:67] op_sel_hi:[1,0]
	v_cvt_pk_bf16_f32 v52, v52, v53
	v_pk_mul_f32 v[50:51], v[50:51], v[66:67] op_sel_hi:[1,0]
	v_cvt_pk_bf16_f32 v53, v54, v55
	v_mov_b32_e32 v244, v52
	v_mov_b32_e32 v245, v53
	v_cvt_pk_bf16_f32 v48, v48, v49
	v_cvt_pk_bf16_f32 v49, v50, v51
	v_mov_b32_e32 v246, v48
	v_mov_b32_e32 v247, v49
	v_and_b32_e32 v242, 16, v190
	v_mul_u32_u24_e32 v242, 3, v242
	v_lshrrev_b32_e32 v242, 1, v242
	v_mov_b32_e32 v243, 0
	v_lshl_add_u64 v[240:241], v[64:65], 0, v[242:243]
	v_permlane16_swap_b32 v248, v250
	v_permlane16_swap_b32 v249, v251
	v_permlane16_swap_b32 v244, v246
	v_permlane16_swap_b32 v245, v247
	flat_store_dwordx4 v[240:241], v[248:251]
	flat_store_dwordx4 v[240:241], v[244:247] offset:64
	ds_read_b32 v50, v104 offset:320
	v_or_b32_e32 v48, 0x50, v100
	v_ashrrev_i32_e32 v49, 31, v48
	v_lshlrev_b64 v[48:49], 11, v[48:49]
	v_lshl_add_u64 v[48:49], v[102:103], 0, v[48:49]
	s_waitcnt lgkmcnt(0)
	v_pk_mul_f32 v[44:45], v[44:45], v[50:51] op_sel_hi:[1,0]
	v_pk_mul_f32 v[40:41], v[40:41], v[50:51] op_sel_hi:[1,0]
	v_pk_mul_f32 v[36:37], v[36:37], v[50:51] op_sel_hi:[1,0]
	v_pk_mul_f32 v[32:33], v[32:33], v[50:51] op_sel_hi:[1,0]
	v_pk_mul_f32 v[46:47], v[46:47], v[50:51] op_sel_hi:[1,0]
	v_cvt_pk_bf16_f32 v44, v44, v45
	v_pk_mul_f32 v[42:43], v[42:43], v[50:51] op_sel_hi:[1,0]
	v_cvt_pk_bf16_f32 v45, v46, v47
	v_mov_b32_e32 v248, v44
	v_mov_b32_e32 v249, v45
	v_cvt_pk_bf16_f32 v40, v40, v41
	v_cvt_pk_bf16_f32 v41, v42, v43
	v_mov_b32_e32 v250, v40
	v_mov_b32_e32 v251, v41
	v_pk_mul_f32 v[38:39], v[38:39], v[50:51] op_sel_hi:[1,0]
	v_cvt_pk_bf16_f32 v36, v36, v37
	v_pk_mul_f32 v[34:35], v[34:35], v[50:51] op_sel_hi:[1,0]
	v_cvt_pk_bf16_f32 v37, v38, v39
	v_mov_b32_e32 v244, v36
	v_mov_b32_e32 v245, v37
	v_cvt_pk_bf16_f32 v32, v32, v33
	v_cvt_pk_bf16_f32 v33, v34, v35
	v_mov_b32_e32 v246, v32
	v_mov_b32_e32 v247, v33
	v_and_b32_e32 v242, 16, v190
	v_mul_u32_u24_e32 v242, 3, v242
	v_lshrrev_b32_e32 v242, 1, v242
	v_mov_b32_e32 v243, 0
	v_lshl_add_u64 v[240:241], v[48:49], 0, v[242:243]
	v_permlane16_swap_b32 v248, v250
	v_permlane16_swap_b32 v249, v251
	v_permlane16_swap_b32 v244, v246
	v_permlane16_swap_b32 v245, v247
	flat_store_dwordx4 v[240:241], v[248:251]
	flat_store_dwordx4 v[240:241], v[244:247] offset:64
	ds_read_b32 v34, v104 offset:384
	v_or_b32_e32 v32, 0x60, v100
	v_ashrrev_i32_e32 v33, 31, v32
	v_lshlrev_b64 v[32:33], 11, v[32:33]
	v_lshl_add_u64 v[32:33], v[102:103], 0, v[32:33]
	s_waitcnt lgkmcnt(0)
	v_pk_mul_f32 v[28:29], v[28:29], v[34:35] op_sel_hi:[1,0]
	v_pk_mul_f32 v[24:25], v[24:25], v[34:35] op_sel_hi:[1,0]
	v_pk_mul_f32 v[20:21], v[20:21], v[34:35] op_sel_hi:[1,0]
	v_pk_mul_f32 v[16:17], v[16:17], v[34:35] op_sel_hi:[1,0]
	v_pk_mul_f32 v[30:31], v[30:31], v[34:35] op_sel_hi:[1,0]
	v_cvt_pk_bf16_f32 v28, v28, v29
	v_pk_mul_f32 v[26:27], v[26:27], v[34:35] op_sel_hi:[1,0]
	v_cvt_pk_bf16_f32 v29, v30, v31
	v_mov_b32_e32 v248, v28
	v_mov_b32_e32 v249, v29
	v_cvt_pk_bf16_f32 v24, v24, v25
	v_cvt_pk_bf16_f32 v25, v26, v27
	v_mov_b32_e32 v250, v24
	v_mov_b32_e32 v251, v25
	v_pk_mul_f32 v[22:23], v[22:23], v[34:35] op_sel_hi:[1,0]
	v_cvt_pk_bf16_f32 v20, v20, v21
	v_pk_mul_f32 v[18:19], v[18:19], v[34:35] op_sel_hi:[1,0]
	v_cvt_pk_bf16_f32 v21, v22, v23
	v_mov_b32_e32 v244, v20
	v_mov_b32_e32 v245, v21
	v_cvt_pk_bf16_f32 v16, v16, v17
	v_cvt_pk_bf16_f32 v17, v18, v19
	v_mov_b32_e32 v246, v16
	v_mov_b32_e32 v247, v17
	v_and_b32_e32 v242, 16, v190
	v_mul_u32_u24_e32 v242, 3, v242
	v_lshrrev_b32_e32 v242, 1, v242
	v_mov_b32_e32 v243, 0
	v_lshl_add_u64 v[240:241], v[32:33], 0, v[242:243]
	v_permlane16_swap_b32 v248, v250
	v_permlane16_swap_b32 v249, v251
	v_permlane16_swap_b32 v244, v246
	v_permlane16_swap_b32 v245, v247
	flat_store_dwordx4 v[240:241], v[248:251]
	flat_store_dwordx4 v[240:241], v[244:247] offset:64
	ds_read_b32 v18, v104 offset:448
	v_or_b32_e32 v16, 0x70, v100
	v_ashrrev_i32_e32 v17, 31, v16
	v_lshlrev_b64 v[16:17], 11, v[16:17]
	v_lshl_add_u64 v[16:17], v[102:103], 0, v[16:17]
	s_waitcnt lgkmcnt(0)
	v_pk_mul_f32 v[12:13], v[12:13], v[18:19] op_sel_hi:[1,0]
	v_pk_mul_f32 v[8:9], v[8:9], v[18:19] op_sel_hi:[1,0]
	v_pk_mul_f32 v[4:5], v[4:5], v[18:19] op_sel_hi:[1,0]
	v_pk_mul_f32 v[0:1], v[0:1], v[18:19] op_sel_hi:[1,0]
	v_pk_mul_f32 v[14:15], v[14:15], v[18:19] op_sel_hi:[1,0]
	v_cvt_pk_bf16_f32 v12, v12, v13
	v_pk_mul_f32 v[10:11], v[10:11], v[18:19] op_sel_hi:[1,0]
	v_cvt_pk_bf16_f32 v13, v14, v15
	v_mov_b32_e32 v248, v12
	v_mov_b32_e32 v249, v13
	v_cvt_pk_bf16_f32 v8, v8, v9
	v_cvt_pk_bf16_f32 v9, v10, v11
	v_mov_b32_e32 v250, v8
	v_mov_b32_e32 v251, v9
	v_pk_mul_f32 v[6:7], v[6:7], v[18:19] op_sel_hi:[1,0]
	v_cvt_pk_bf16_f32 v4, v4, v5
	v_pk_mul_f32 v[2:3], v[2:3], v[18:19] op_sel_hi:[1,0]
	v_cvt_pk_bf16_f32 v5, v6, v7
	v_mov_b32_e32 v244, v4
	v_mov_b32_e32 v245, v5
	v_cvt_pk_bf16_f32 v0, v0, v1
	v_cvt_pk_bf16_f32 v1, v2, v3
	v_mov_b32_e32 v246, v0
	v_mov_b32_e32 v247, v1
	v_and_b32_e32 v242, 16, v190
	v_mul_u32_u24_e32 v242, 3, v242
	v_lshrrev_b32_e32 v242, 1, v242
	v_mov_b32_e32 v243, 0
	v_lshl_add_u64 v[240:241], v[16:17], 0, v[242:243]
	v_permlane16_swap_b32 v248, v250
	v_permlane16_swap_b32 v249, v251
	v_permlane16_swap_b32 v244, v246
	v_permlane16_swap_b32 v245, v247
	flat_store_dwordx4 v[240:241], v[248:251]
	flat_store_dwordx4 v[240:241], v[244:247] offset:64
	s_cbranch_scc0 .LBB0_235

.LBB0_271:
	s_add_u32 s2, s34, s22
	s_addc_u32 s3, s35, s23
	v_lshlrev_b32_e32 v144, 1, v98
	v_lshl_add_u64 v[0:1], s[2:3], 0, v[144:145]
	v_lshlrev_b32_e32 v144, 1, v106
	v_lshl_add_u64 v[0:1], v[0:1], 0, v[144:145]
	v_lshlrev_b64 v[2:3], 11, v[96:97]
	v_lshl_add_u64 v[2:3], v[0:1], 0, v[2:3]
	v_cvt_pk_bf16_f32 v4, v174, v175
	v_cvt_pk_bf16_f32 v5, v172, v173
	v_mov_b32_e32 v248, v4
	v_mov_b32_e32 v249, v5
	v_cvt_pk_bf16_f32 v4, v170, v171
	v_cvt_pk_bf16_f32 v5, v168, v169
	v_mov_b32_e32 v250, v4
	v_mov_b32_e32 v251, v5
	v_and_b32_e32 v242, 16, v190
	v_mul_u32_u24_e32 v242, 3, v242
	v_lshrrev_b32_e32 v242, 1, v242
	v_mov_b32_e32 v243, 0
	v_lshl_add_u64 v[240:241], v[2:3], 0, v[242:243]
	v_permlane16_swap_b32 v248, v250
	v_permlane16_swap_b32 v249, v251
	flat_store_dwordx4 v[240:241], v[248:251]
	v_lshlrev_b64 v[2:3], 11, v[100:101]
	v_lshl_add_u64 v[2:3], v[0:1], 0, v[2:3]
	v_cvt_pk_bf16_f32 v4, v166, v167
	v_cvt_pk_bf16_f32 v5, v164, v165
	v_mov_b32_e32 v248, v4
	v_mov_b32_e32 v249, v5
	v_cvt_pk_bf16_f32 v4, v162, v163
	v_cvt_pk_bf16_f32 v5, v160, v161
	v_mov_b32_e32 v250, v4
	v_mov_b32_e32 v251, v5
	v_and_b32_e32 v242, 16, v190
	v_mul_u32_u24_e32 v242, 3, v242
	v_lshrrev_b32_e32 v242, 1, v242
	v_mov_b32_e32 v243, 0
	v_lshl_add_u64 v[240:241], v[2:3], 0, v[242:243]
	v_permlane16_swap_b32 v248, v250
	v_permlane16_swap_b32 v249, v251
	flat_store_dwordx4 v[240:241], v[248:251]
	v_lshlrev_b64 v[2:3], 11, v[90:91]
	v_lshl_add_u64 v[2:3], v[0:1], 0, v[2:3]
	v_cvt_pk_bf16_f32 v4, v158, v159
	v_cvt_pk_bf16_f32 v5, v156, v157
	v_mov_b32_e32 v248, v4
	v_mov_b32_e32 v249, v5
	v_cvt_pk_bf16_f32 v4, v140, v141
	v_cvt_pk_bf16_f32 v5, v138, v139
	v_mov_b32_e32 v250, v4
	v_mov_b32_e32 v251, v5
	v_and_b32_e32 v242, 16, v190
	v_mul_u32_u24_e32 v242, 3, v242
	v_lshrrev_b32_e32 v242, 1, v242
	v_mov_b32_e32 v243, 0
	v_lshl_add_u64 v[240:241], v[2:3], 0, v[242:243]
	v_permlane16_swap_b32 v248, v250
	v_permlane16_swap_b32 v249, v251
	flat_store_dwordx4 v[240:241], v[248:251]
	v_lshlrev_b64 v[2:3], 11, v[88:89]
	v_lshl_add_u64 v[2:3], v[0:1], 0, v[2:3]
	v_cvt_pk_bf16_f32 v4, v132, v133
	v_cvt_pk_bf16_f32 v5, v130, v131
	v_mov_b32_e32 v248, v4
	v_mov_b32_e32 v249, v5
	v_cvt_pk_bf16_f32 v4, v124, v125
	v_cvt_pk_bf16_f32 v5, v122, v123
	v_mov_b32_e32 v250, v4
	v_mov_b32_e32 v251, v5
	v_and_b32_e32 v242, 16, v190
	v_mul_u32_u24_e32 v242, 3, v242
	v_lshrrev_b32_e32 v242, 1, v242
	v_mov_b32_e32 v243, 0
	v_lshl_add_u64 v[240:241], v[2:3], 0, v[242:243]
	v_permlane16_swap_b32 v248, v250
	v_permlane16_swap_b32 v249, v251
	flat_store_dwordx4 v[240:241], v[248:251]
	v_lshlrev_b64 v[2:3], 11, v[82:83]
	v_lshl_add_u64 v[2:3], v[0:1], 0, v[2:3]
	v_cvt_pk_bf16_f32 v4, v116, v117
	v_cvt_pk_bf16_f32 v5, v114, v115
	v_mov_b32_e32 v248, v4
	v_mov_b32_e32 v249, v5
	v_cvt_pk_bf16_f32 v4, v110, v111
	v_cvt_pk_bf16_f32 v5, v108, v109
	v_mov_b32_e32 v250, v4
	v_mov_b32_e32 v251, v5
	v_and_b32_e32 v242, 16, v190
	v_mul_u32_u24_e32 v242, 3, v242
	v_lshrrev_b32_e32 v242, 1, v242
	v_mov_b32_e32 v243, 0
	v_lshl_add_u64 v[240:241], v[2:3], 0, v[242:243]
	v_permlane16_swap_b32 v248, v250
	v_permlane16_swap_b32 v249, v251
	flat_store_dwordx4 v[240:241], v[248:251]
	v_lshlrev_b64 v[2:3], 11, v[76:77]
	v_lshl_add_u64 v[2:3], v[0:1], 0, v[2:3]
	v_cvt_pk_bf16_f32 v4, v104, v105
	v_cvt_pk_bf16_f32 v5, v102, v103
	v_mov_b32_e32 v248, v4
	v_mov_b32_e32 v249, v5
	v_cvt_pk_bf16_f32 v4, v94, v95
	v_cvt_pk_bf16_f32 v5, v92, v93
	v_mov_b32_e32 v250, v4
	v_mov_b32_e32 v251, v5
	v_and_b32_e32 v242, 16, v190
	v_mul_u32_u24_e32 v242, 3, v242
	v_lshrrev_b32_e32 v242, 1, v242
	v_mov_b32_e32 v243, 0
	v_lshl_add_u64 v[240:241], v[2:3], 0, v[242:243]
	v_permlane16_swap_b32 v248, v250
	v_permlane16_swap_b32 v249, v251
	flat_store_dwordx4 v[240:241], v[248:251]
	v_lshlrev_b64 v[2:3], 11, v[70:71]
	v_lshl_add_u64 v[2:3], v[0:1], 0, v[2:3]
	v_cvt_pk_bf16_f32 v4, v86, v87
	v_cvt_pk_bf16_f32 v5, v84, v85
	v_mov_b32_e32 v248, v4
	v_mov_b32_e32 v249, v5
	v_cvt_pk_bf16_f32 v4, v80, v81
	v_cvt_pk_bf16_f32 v5, v78, v79
	v_mov_b32_e32 v250, v4
	v_mov_b32_e32 v251, v5
	v_and_b32_e32 v242, 16, v190
	v_mul_u32_u24_e32 v242, 3, v242
	v_lshrrev_b32_e32 v242, 1, v242
	v_mov_b32_e32 v243, 0
	v_lshl_add_u64 v[240:241], v[2:3], 0, v[242:243]
	v_permlane16_swap_b32 v248, v250
	v_permlane16_swap_b32 v249, v251
	flat_store_dwordx4 v[240:241], v[248:251]
	v_lshlrev_b64 v[2:3], 11, v[64:65]
	v_readlane_b32 s2, v255, 6
	v_lshl_add_u64 v[0:1], v[0:1], 0, v[2:3]
	v_cvt_pk_bf16_f32 v2, v74, v75
	v_cvt_pk_bf16_f32 v3, v72, v73
	s_add_i32 s63, s63, s2
	s_and_b64 vcc, exec, s[6:7]
	v_readlane_b32 s72, v255, 23
	v_mov_b32_e32 v248, v2
	v_mov_b32_e32 v249, v3
	v_cvt_pk_bf16_f32 v2, v66, v67
	v_cvt_pk_bf16_f32 v3, v68, v69
	v_mov_b32_e32 v250, v2
	v_mov_b32_e32 v251, v3
	v_and_b32_e32 v242, 16, v190
	v_mul_u32_u24_e32 v242, 3, v242
	v_lshrrev_b32_e32 v242, 1, v242
	v_mov_b32_e32 v243, 0
	v_lshl_add_u64 v[240:241], v[0:1], 0, v[242:243]
	v_permlane16_swap_b32 v248, v250
	v_permlane16_swap_b32 v249, v251
	flat_store_dwordx4 v[240:241], v[248:251]
	v_readlane_b32 s3, v255, 7
	s_cbranch_vccnz .LBB0_280

.LBB0_678:
	s_or_saveexec_b64 s[22:23], s[22:23]
	v_ashrrev_i32_e32 v131, 31, v130
	v_lshl_add_u64 v[130:131], v[130:131], 1, s[12:13]
	v_lshlrev_b32_e32 v144, 1, v129
	v_lshl_add_u64 v[130:131], v[130:131], 0, v[144:145]
	s_xor_b64 exec, exec, s[22:23]
	s_cbranch_execz .LBB0_680
	v_ashrrev_i32_e32 v129, 31, v128
	v_lshlrev_b64 v[136:137], 11, v[128:129]
	v_lshl_add_u64 v[136:137], v[130:131], 0, v[136:137]
	v_cvt_pk_bf16_f32 v124, v124, v125
	v_cvt_pk_bf16_f32 v125, v126, v127
	s_waitcnt vmcnt(0)
	v_mov_b32_e32 v248, v124
	v_mov_b32_e32 v249, v125
	v_cvt_pk_bf16_f32 v120, v120, v121
	v_cvt_pk_bf16_f32 v121, v122, v123
	v_mov_b32_e32 v250, v120
	v_mov_b32_e32 v251, v121
	v_cvt_pk_bf16_f32 v116, v116, v117
	v_cvt_pk_bf16_f32 v117, v118, v119
	v_mov_b32_e32 v244, v116
	v_mov_b32_e32 v245, v117
	v_cvt_pk_bf16_f32 v112, v112, v113
	v_cvt_pk_bf16_f32 v113, v114, v115
	v_mov_b32_e32 v246, v112
	v_mov_b32_e32 v247, v113
	v_and_b32_e32 v242, 16, v190
	v_mul_u32_u24_e32 v242, 3, v242
	v_lshrrev_b32_e32 v242, 1, v242
	v_mov_b32_e32 v243, 0
	v_lshl_add_u64 v[240:241], v[136:137], 0, v[242:243]
	v_permlane16_swap_b32 v248, v250
	v_permlane16_swap_b32 v249, v251
	v_permlane16_swap_b32 v244, v246
	v_permlane16_swap_b32 v245, v247
	flat_store_dwordx4 v[240:241], v[248:251]
	flat_store_dwordx4 v[240:241], v[244:247] offset:64

.LBB0_682:
	s_andn2_saveexec_b64 s[22:23], s[22:23]
	s_cbranch_execz .LBB0_684
	v_ashrrev_i32_e32 v113, 31, v112
	v_lshlrev_b64 v[112:113], 11, v[112:113]
	v_lshl_add_u64 v[112:113], v[130:131], 0, v[112:113]
	v_cvt_pk_bf16_f32 v108, v108, v109
	v_cvt_pk_bf16_f32 v109, v110, v111
	s_waitcnt vmcnt(0)
	v_mov_b32_e32 v248, v108
	v_mov_b32_e32 v249, v109
	v_cvt_pk_bf16_f32 v104, v104, v105
	v_cvt_pk_bf16_f32 v105, v106, v107
	v_mov_b32_e32 v250, v104
	v_mov_b32_e32 v251, v105
	v_cvt_pk_bf16_f32 v100, v100, v101
	v_cvt_pk_bf16_f32 v101, v102, v103
	v_mov_b32_e32 v244, v100
	v_mov_b32_e32 v245, v101
	v_cvt_pk_bf16_f32 v96, v96, v97
	v_cvt_pk_bf16_f32 v97, v98, v99
	v_mov_b32_e32 v246, v96
	v_mov_b32_e32 v247, v97
	v_and_b32_e32 v242, 16, v190
	v_mul_u32_u24_e32 v242, 3, v242
	v_lshrrev_b32_e32 v242, 1, v242
	v_mov_b32_e32 v243, 0
	v_lshl_add_u64 v[240:241], v[112:113], 0, v[242:243]
	v_permlane16_swap_b32 v248, v250
	v_permlane16_swap_b32 v249, v251
	v_permlane16_swap_b32 v244, v246
	v_permlane16_swap_b32 v245, v247
	flat_store_dwordx4 v[240:241], v[248:251]
	flat_store_dwordx4 v[240:241], v[244:247] offset:64

.LBB0_686:
	s_andn2_saveexec_b64 s[22:23], s[22:23]
	s_cbranch_execz .LBB0_688
	v_ashrrev_i32_e32 v97, 31, v96
	v_lshlrev_b64 v[96:97], 11, v[96:97]
	v_lshl_add_u64 v[96:97], v[130:131], 0, v[96:97]
	v_cvt_pk_bf16_f32 v92, v92, v93
	v_cvt_pk_bf16_f32 v93, v94, v95
	s_waitcnt vmcnt(0)
	v_mov_b32_e32 v248, v92
	v_mov_b32_e32 v249, v93
	v_cvt_pk_bf16_f32 v88, v88, v89
	v_cvt_pk_bf16_f32 v89, v90, v91
	v_mov_b32_e32 v250, v88
	v_mov_b32_e32 v251, v89
	v_cvt_pk_bf16_f32 v84, v84, v85
	v_cvt_pk_bf16_f32 v85, v86, v87
	v_mov_b32_e32 v244, v84
	v_mov_b32_e32 v245, v85
	v_cvt_pk_bf16_f32 v80, v80, v81
	v_cvt_pk_bf16_f32 v81, v82, v83
	v_mov_b32_e32 v246, v80
	v_mov_b32_e32 v247, v81
	v_and_b32_e32 v242, 16, v190
	v_mul_u32_u24_e32 v242, 3, v242
	v_lshrrev_b32_e32 v242, 1, v242
	v_mov_b32_e32 v243, 0
	v_lshl_add_u64 v[240:241], v[96:97], 0, v[242:243]
	v_permlane16_swap_b32 v248, v250
	v_permlane16_swap_b32 v249, v251
	v_permlane16_swap_b32 v244, v246
	v_permlane16_swap_b32 v245, v247
	flat_store_dwordx4 v[240:241], v[248:251]
	flat_store_dwordx4 v[240:241], v[244:247] offset:64

.LBB0_690:
	s_andn2_saveexec_b64 s[22:23], s[22:23]
	s_cbranch_execz .LBB0_692
	v_ashrrev_i32_e32 v81, 31, v80
	v_lshlrev_b64 v[80:81], 11, v[80:81]
	v_lshl_add_u64 v[80:81], v[130:131], 0, v[80:81]
	v_cvt_pk_bf16_f32 v76, v76, v77
	v_cvt_pk_bf16_f32 v77, v78, v79
	s_waitcnt vmcnt(0)
	v_mov_b32_e32 v248, v76
	v_mov_b32_e32 v249, v77
	v_cvt_pk_bf16_f32 v72, v72, v73
	v_cvt_pk_bf16_f32 v73, v74, v75
	v_mov_b32_e32 v250, v72
	v_mov_b32_e32 v251, v73
	v_cvt_pk_bf16_f32 v68, v68, v69
	v_cvt_pk_bf16_f32 v69, v70, v71
	v_mov_b32_e32 v244, v68
	v_mov_b32_e32 v245, v69
	v_cvt_pk_bf16_f32 v64, v64, v65
	v_cvt_pk_bf16_f32 v65, v66, v67
	v_mov_b32_e32 v246, v64
	v_mov_b32_e32 v247, v65
	v_and_b32_e32 v242, 16, v190
	v_mul_u32_u24_e32 v242, 3, v242
	v_lshrrev_b32_e32 v242, 1, v242
	v_mov_b32_e32 v243, 0
	v_lshl_add_u64 v[240:241], v[80:81], 0, v[242:243]
	v_permlane16_swap_b32 v248, v250
	v_permlane16_swap_b32 v249, v251
	v_permlane16_swap_b32 v244, v246
	v_permlane16_swap_b32 v245, v247
	flat_store_dwordx4 v[240:241], v[248:251]
	flat_store_dwordx4 v[240:241], v[244:247] offset:64

.LBB0_694:
	s_andn2_saveexec_b64 s[22:23], s[22:23]
	s_cbranch_execz .LBB0_696
	v_ashrrev_i32_e32 v65, 31, v64
	v_lshlrev_b64 v[64:65], 11, v[64:65]
	v_lshl_add_u64 v[64:65], v[130:131], 0, v[64:65]
	v_cvt_pk_bf16_f32 v60, v60, v61
	v_cvt_pk_bf16_f32 v61, v62, v63
	s_waitcnt vmcnt(0)
	v_mov_b32_e32 v248, v60
	v_mov_b32_e32 v249, v61
	v_cvt_pk_bf16_f32 v56, v56, v57
	v_cvt_pk_bf16_f32 v57, v58, v59
	v_mov_b32_e32 v250, v56
	v_mov_b32_e32 v251, v57
	v_cvt_pk_bf16_f32 v52, v52, v53
	v_cvt_pk_bf16_f32 v53, v54, v55
	v_mov_b32_e32 v244, v52
	v_mov_b32_e32 v245, v53
	v_cvt_pk_bf16_f32 v48, v48, v49
	v_cvt_pk_bf16_f32 v49, v50, v51
	v_mov_b32_e32 v246, v48
	v_mov_b32_e32 v247, v49
	v_and_b32_e32 v242, 16, v190
	v_mul_u32_u24_e32 v242, 3, v242
	v_lshrrev_b32_e32 v242, 1, v242
	v_mov_b32_e32 v243, 0
	v_lshl_add_u64 v[240:241], v[64:65], 0, v[242:243]
	v_permlane16_swap_b32 v248, v250
	v_permlane16_swap_b32 v249, v251
	v_permlane16_swap_b32 v244, v246
	v_permlane16_swap_b32 v245, v247
	flat_store_dwordx4 v[240:241], v[248:251]
	flat_store_dwordx4 v[240:241], v[244:247] offset:64

.LBB0_698:
	s_andn2_saveexec_b64 s[22:23], s[22:23]
	s_cbranch_execz .LBB0_700
	v_ashrrev_i32_e32 v49, 31, v48
	v_lshlrev_b64 v[48:49], 11, v[48:49]
	v_lshl_add_u64 v[48:49], v[130:131], 0, v[48:49]
	v_cvt_pk_bf16_f32 v44, v44, v45
	v_cvt_pk_bf16_f32 v45, v46, v47
	s_waitcnt vmcnt(0)
	v_mov_b32_e32 v248, v44
	v_mov_b32_e32 v249, v45
	v_cvt_pk_bf16_f32 v40, v40, v41
	v_cvt_pk_bf16_f32 v41, v42, v43
	v_mov_b32_e32 v250, v40
	v_mov_b32_e32 v251, v41
	v_cvt_pk_bf16_f32 v36, v36, v37
	v_cvt_pk_bf16_f32 v37, v38, v39
	v_mov_b32_e32 v244, v36
	v_mov_b32_e32 v245, v37
	v_cvt_pk_bf16_f32 v32, v32, v33
	v_cvt_pk_bf16_f32 v33, v34, v35
	v_mov_b32_e32 v246, v32
	v_mov_b32_e32 v247, v33
	v_and_b32_e32 v242, 16, v190
	v_mul_u32_u24_e32 v242, 3, v242
	v_lshrrev_b32_e32 v242, 1, v242
	v_mov_b32_e32 v243, 0
	v_lshl_add_u64 v[240:241], v[48:49], 0, v[242:243]
	v_permlane16_swap_b32 v248, v250
	v_permlane16_swap_b32 v249, v251
	v_permlane16_swap_b32 v244, v246
	v_permlane16_swap_b32 v245, v247
	flat_store_dwordx4 v[240:241], v[248:251]
	flat_store_dwordx4 v[240:241], v[244:247] offset:64

.LBB0_702:
	s_andn2_saveexec_b64 s[22:23], s[22:23]
	s_cbranch_execz .LBB0_704
	v_ashrrev_i32_e32 v33, 31, v32
	v_lshlrev_b64 v[32:33], 11, v[32:33]
	v_lshl_add_u64 v[32:33], v[130:131], 0, v[32:33]
	v_cvt_pk_bf16_f32 v28, v28, v29
	v_cvt_pk_bf16_f32 v29, v30, v31
	s_waitcnt vmcnt(0)
	v_mov_b32_e32 v248, v28
	v_mov_b32_e32 v249, v29
	v_cvt_pk_bf16_f32 v24, v24, v25
	v_cvt_pk_bf16_f32 v25, v26, v27
	v_mov_b32_e32 v250, v24
	v_mov_b32_e32 v251, v25
	v_cvt_pk_bf16_f32 v20, v20, v21
	v_cvt_pk_bf16_f32 v21, v22, v23
	v_mov_b32_e32 v244, v20
	v_mov_b32_e32 v245, v21
	v_cvt_pk_bf16_f32 v16, v16, v17
	v_cvt_pk_bf16_f32 v17, v18, v19
	v_mov_b32_e32 v246, v16
	v_mov_b32_e32 v247, v17
	v_and_b32_e32 v242, 16, v190
	v_mul_u32_u24_e32 v242, 3, v242
	v_lshrrev_b32_e32 v242, 1, v242
	v_mov_b32_e32 v243, 0
	v_lshl_add_u64 v[240:241], v[32:33], 0, v[242:243]
	v_permlane16_swap_b32 v248, v250
	v_permlane16_swap_b32 v249, v251
	v_permlane16_swap_b32 v244, v246
	v_permlane16_swap_b32 v245, v247
	flat_store_dwordx4 v[240:241], v[248:251]
	flat_store_dwordx4 v[240:241], v[244:247] offset:64

.LBB0_706:
	s_andn2_saveexec_b64 s[22:23], s[22:23]
	s_cbranch_execz .LBB0_652
	v_ashrrev_i32_e32 v17, 31, v16
	v_lshlrev_b64 v[16:17], 11, v[16:17]
	v_lshl_add_u64 v[16:17], v[130:131], 0, v[16:17]
	v_cvt_pk_bf16_f32 v12, v12, v13
	v_cvt_pk_bf16_f32 v13, v14, v15
	s_waitcnt vmcnt(0)
	v_mov_b32_e32 v248, v12
	v_mov_b32_e32 v249, v13
	v_cvt_pk_bf16_f32 v8, v8, v9
	v_cvt_pk_bf16_f32 v9, v10, v11
	v_mov_b32_e32 v250, v8
	v_mov_b32_e32 v251, v9
	v_cvt_pk_bf16_f32 v4, v4, v5
	v_cvt_pk_bf16_f32 v5, v6, v7
	v_mov_b32_e32 v244, v4
	v_mov_b32_e32 v245, v5
	v_cvt_pk_bf16_f32 v0, v0, v1
	v_cvt_pk_bf16_f32 v1, v2, v3
	v_mov_b32_e32 v246, v0
	v_mov_b32_e32 v247, v1
	v_and_b32_e32 v242, 16, v190
	v_mul_u32_u24_e32 v242, 3, v242
	v_lshrrev_b32_e32 v242, 1, v242
	v_mov_b32_e32 v243, 0
	v_lshl_add_u64 v[240:241], v[16:17], 0, v[242:243]
	v_permlane16_swap_b32 v248, v250
	v_permlane16_swap_b32 v249, v251
	v_permlane16_swap_b32 v244, v246
	v_permlane16_swap_b32 v245, v247
	flat_store_dwordx4 v[240:241], v[248:251]
	flat_store_dwordx4 v[240:241], v[244:247] offset:64
	s_branch .LBB0_652
